# G1 epilogue: per-row sum-of-squares partials fetched with one dwordx4 per row (lane group g takes 4 of the 16 partials) and summed across lane groups, all 8 rows loaded at the top; 8 loads per wave in
# speedup vs baseline: 1.0164x; 1.0164x over previous
;     __device__ __forceinline__ void apply(const Ld& d, int row, int c0, int, int, int, const f32x4& a0, const f32x4& b0, const f32x4& a1, const f32x4& b1) const { half(d.g0, row, c0, a0, b0); half(d.g1, row, c0 + 128, a1, b1); }
;     __device__ __forceinline__ void apply(const Ld& d, int row, int c0, int, int, int, const f32x4& a0, const f32x4& b0, const f32x4& a1, const f32x4& b1) const { half(d.g0, d.p0, row, c0, a0, b0); half(d.g1, d.p1, row, c0 + 128, a1, b1); }
;     __device__ __forceinline__ void operator()(const f32x4 (&acc)[2][2][4][2], const Unit& u, int wr, int wc, int fr, int fq) const {
;         const int c0 = u.pn * BM + wc * 32 + 8 * fq;
; #pragma unroll
;         for (int ai = 0; ai < 2; ++ai)
; #pragma unroll
;             for (int mp = 0; mp < 4; mp += 2) {
;                 typename F::Ld ld[2];
; #pragma unroll
;                 for (int m = 0; m < 2; ++m) f.load(ld[m], u.pm * BM + ai * HALF + wr * 64 + (mp + m) * 16 + fr, c0, u.pn, fq);
; #pragma unroll
;                 for (int m = 0; m < 2; ++m) f.apply(ld[m], u.pm * BM + ai * HALF + wr * 64 + (mp + m) * 16 + fr, c0, u.pn, wc, fq, acc[ai][0][mp + m][0], acc[ai][0][mp + m][1], acc[ai][1][mp + m][0], acc[ai][1][mp + m][1]);
;     __device__ __forceinline__ void load(Ld& d, int row, int, int, int) const {
; #pragma unroll
;         for (int i = 0; i < 4; ++i) d.p[i] = ((const f32x4*)(ssqh + (size_t)row * 16))[i]; }
;     __device__ __forceinline__ void apply(const Ld& d, int row, int c0, int pn, int wc, int fq, const f32x4& a0, const f32x4& b0, const f32x4& a1, const f32x4& b1) const {
;         const f32x4 t = (d.p[0] + d.p[1]) + (d.p[2] + d.p[3]);
;         const float inv = __builtin_amdgcn_rsqf(((t[0] + t[1]) + (t[2] + t[3])) * (1.f / DM) + EPS);
;         const f32x4 v0 = a0 * inv, v1 = b0 * inv, v2 = a1 * inv, v3 = b1 * inv;
.LBB0_295:
	s_andn2_b64 vcc, exec, s[0:1]
	s_cbranch_vccnz .LBB0_432
	s_lshl_b32 s63, s63, 8
	v_add_u32_e32 v152, s63, v17
	v_ashrrev_i32_e32 v153, 31, v152
	v_lshlrev_b64 v[158:159], 6, v[152:153]
	v_and_b32_e32 v183, 0x30, v228
	v_or_b32_e32 v230, v158, v183
	v_mov_b32_e32 v231, v159
	v_lshl_add_u64 v[180:181], s[24:25], 0, v[230:231]
	s_movk_i32 s50, 0x2000
	s_mov_b32 s51, 0
	v_lshl_add_u64 v[230:231], v[180:181], 0, s[50:51]
	global_load_dwordx4 v[134:137], v[180:181], off
	global_load_dwordx4 v[138:141], v[180:181], off offset:1024
	global_load_dwordx4 v[142:145], v[180:181], off offset:2048
	global_load_dwordx4 v[146:149], v[180:181], off offset:3072
	global_load_dwordx4 v[154:157], v[230:231], off
	global_load_dwordx4 v[160:163], v[230:231], off offset:1024
	global_load_dwordx4 v[164:167], v[230:231], off offset:2048
	global_load_dwordx4 v[168:171], v[230:231], off offset:3072
	s_waitcnt vmcnt(7)
	v_add_f32_e32 v204, v134, v135
	v_add_f32_e32 v212, v136, v137
	s_waitcnt vmcnt(6)
	v_add_f32_e32 v205, v138, v139
	v_add_f32_e32 v213, v140, v141
	s_waitcnt vmcnt(5)
	v_add_f32_e32 v206, v142, v143
	v_add_f32_e32 v214, v144, v145
	s_waitcnt vmcnt(4)
	v_add_f32_e32 v207, v146, v147
	v_add_f32_e32 v215, v148, v149
	s_waitcnt vmcnt(3)
	v_add_f32_e32 v208, v154, v155
	v_add_f32_e32 v216, v156, v157
	s_waitcnt vmcnt(2)
	v_add_f32_e32 v209, v160, v161
	v_add_f32_e32 v217, v162, v163
	s_waitcnt vmcnt(1)
	v_add_f32_e32 v210, v164, v165
	v_add_f32_e32 v218, v166, v167
	s_waitcnt vmcnt(0)
	v_add_f32_e32 v211, v168, v169
	v_add_f32_e32 v219, v170, v171
	v_add_f32_e32 v204, v204, v212
	v_add_f32_e32 v205, v205, v213
	v_add_f32_e32 v206, v206, v214
	v_add_f32_e32 v207, v207, v215
	v_add_f32_e32 v208, v208, v216
	v_add_f32_e32 v209, v209, v217
	v_add_f32_e32 v210, v210, v218
	v_add_f32_e32 v211, v211, v219
	ds_swizzle_b32 v212, v204 offset:swizzle(SWAP,16)
	ds_swizzle_b32 v213, v205 offset:swizzle(SWAP,16)
	ds_swizzle_b32 v214, v206 offset:swizzle(SWAP,16)
	ds_swizzle_b32 v215, v207 offset:swizzle(SWAP,16)
	ds_swizzle_b32 v216, v208 offset:swizzle(SWAP,16)
	ds_swizzle_b32 v217, v209 offset:swizzle(SWAP,16)
	ds_swizzle_b32 v218, v210 offset:swizzle(SWAP,16)
	ds_swizzle_b32 v219, v211 offset:swizzle(SWAP,16)
	s_waitcnt lgkmcnt(0)
	v_add_f32_e32 v204, v204, v212
	v_add_f32_e32 v205, v205, v213
	v_add_f32_e32 v206, v206, v214
	v_add_f32_e32 v207, v207, v215
	v_add_f32_e32 v208, v208, v216
	v_add_f32_e32 v209, v209, v217
	v_add_f32_e32 v210, v210, v218
	v_add_f32_e32 v211, v211, v219
	v_mov_b32_e32 v212, v204
	v_mov_b32_e32 v213, v205
	v_mov_b32_e32 v214, v206
	v_mov_b32_e32 v215, v207
	v_mov_b32_e32 v216, v208
	v_mov_b32_e32 v217, v209
	v_mov_b32_e32 v218, v210
	v_mov_b32_e32 v219, v211
	s_nop 1
	v_permlane32_swap_b32_e32 v204, v212
	v_permlane32_swap_b32_e32 v205, v213
	v_permlane32_swap_b32_e32 v206, v214
	v_permlane32_swap_b32_e32 v207, v215
	v_permlane32_swap_b32_e32 v208, v216
	v_permlane32_swap_b32_e32 v209, v217
	v_permlane32_swap_b32_e32 v210, v218
	v_permlane32_swap_b32_e32 v211, v219
	v_add_f32_e32 v172, v204, v212
	v_add_f32_e32 v173, v205, v213
	v_add_f32_e32 v174, v206, v214
	v_add_f32_e32 v175, v207, v215
	v_add_f32_e32 v176, v208, v216
	v_add_f32_e32 v177, v209, v217
	v_add_f32_e32 v178, v210, v218
	v_add_f32_e32 v179, v211, v219
	v_fmamk_f32 v172, v172, 0x3a800000, v229
	v_fmamk_f32 v173, v173, 0x3a800000, v229
	v_fmamk_f32 v174, v174, 0x3a800000, v229
	v_fmamk_f32 v175, v175, 0x3a800000, v229
	v_fmamk_f32 v176, v176, 0x3a800000, v229
	v_fmamk_f32 v177, v177, 0x3a800000, v229
	v_fmamk_f32 v178, v178, 0x3a800000, v229
	v_fmamk_f32 v179, v179, 0x3a800000, v229
	v_rsq_f32_e32 v172, v172
	v_rsq_f32_e32 v173, v173
	v_rsq_f32_e32 v174, v174
	v_rsq_f32_e32 v175, v175
	v_rsq_f32_e32 v176, v176
	v_rsq_f32_e32 v177, v177
	v_rsq_f32_e32 v178, v178
	v_rsq_f32_e32 v179, v179
	v_or_b32_e32 v134, 16, v152
	v_ashrrev_i32_e32 v135, 31, v134
	v_lshlrev_b64 v[134:135], 6, v[134:135]
	v_lshl_add_u64 v[146:147], s[24:25], 0, v[134:135]
	v_lshl_or_b32 v150, s71, 8, v241
	s_movk_i32 s0, 0x1220
	s_cmp_gt_i32 s71, 17
	v_cmp_gt_i32_e64 s[40:41], s0, v150
	s_cselect_b64 s[0:1], -1, 0
	s_and_b64 vcc, exec, s[0:1]
	v_mov_b32_e32 v0, v172
	s_nop 0
	v_pk_mul_f32 v[132:133], v[132:133], v[0:1] op_sel_hi:[1,0]
	v_pk_mul_f32 v[130:131], v[130:131], v[0:1] op_sel_hi:[1,0]
	v_pk_mul_f32 v[154:155], v[128:129], v[0:1] op_sel_hi:[1,0]
	v_pk_mul_f32 v[156:157], v[126:127], v[0:1] op_sel_hi:[1,0]
	s_cbranch_vccz .LBB0_309
	s_mov_b64 s[42:43], 0
	s_mov_b64 s[22:23], 0
	s_and_saveexec_b64 s[44:45], s[40:41]
	s_xor_b64 s[44:45], exec, s[44:45]
	s_cbranch_execz .LBB0_299
	v_readlane_b32 s36, v255, 22
	v_readlane_b32 s37, v255, 23
	s_mov_b64 s[22:23], exec
	v_cvt_pk_bf16_f32 v126, v130, v131
	v_cvt_pk_bf16_f32 v127, v132, v133
	v_cvt_pk_bf16_f32 v128, v156, v157
	v_cvt_pk_bf16_f32 v129, v154, v155
	s_nop 0
	v_lshl_add_u64 v[160:161], s[36:37], 0, v[158:159]
